# c34: c31 + DPP row_ror:8/quad_perm replace xor-8,2,1 bpermute steps of P10 and final RMSNorm row sums (bit-identical pairing)
# speedup vs baseline: 1.0076x; 1.0076x over previous
.LBB0_620:
	s_or_b64 exec, exec, s[4:5]
	v_lshlrev_b64 v[0:1], v4, v[0:1]
	v_lshl_add_u64 v[0:1], v[6:7], 0, v[0:1]
	v_lshlrev_b64 v[2:3], 12, v[2:3]
	v_lshl_add_u64 v[0:1], v[0:1], 0, v[2:3]
	v_lshl_add_u64 v[64:65], v[0:1], 0, v[26:27]
	global_load_dwordx4 v[12:15], v[64:65], off nt
	global_load_dwordx4 v[8:11], v[64:65], off offset:1024 nt
	global_load_dwordx4 v[4:7], v[64:65], off offset:2048 nt
	global_load_dwordx4 v[0:3], v[64:65], off offset:3072 nt
	v_ashrrev_i32_e32 v40, 13, v40
	v_lshl_add_u64 v[38:39], s[28:29], 0, v[38:39]
	s_mov_b64 s[4:5], 0x1000
	v_lshl_add_u64 v[66:67], v[38:39], 0, s[4:5]
	v_lshl_add_u64 v[38:39], v[38:39], 0, v[26:27]
	v_lshl_add_u64 v[68:69], v[66:67], 0, v[26:27]
	global_load_dwordx4 v[72:75], v[38:39], off
	global_load_dwordx4 v[88:91], v[68:69], off
	v_lshl_add_u64 v[68:69], v[66:67], 0, v[32:33]
	global_load_dwordx4 v[76:79], v[38:39], off offset:1024
	global_load_dwordx4 v[92:95], v[68:69], off
	v_lshl_add_u64 v[68:69], v[66:67], 0, v[34:35]
	global_load_dwordx4 v[80:83], v[38:39], off offset:2048
	global_load_dwordx4 v[96:99], v[68:69], off
	v_lshl_add_u64 v[68:69], v[66:67], 0, v[36:37]
	global_load_dwordx4 v[84:87], v[38:39], off offset:3072
	global_load_dwordx4 v[100:103], v[68:69], off
	s_mov_b32 s4, 0x800000
	s_waitcnt vmcnt(11)
	v_mov_b32_e32 v120, v13
	s_waitcnt vmcnt(10)
	v_mov_b32_e32 v121, v9
	v_mov_b32_e32 v122, v12
	v_mov_b32_e32 v123, v8
	v_pk_mul_f32 v[120:121], v[120:121], v[120:121]
	s_nop 0
	v_pk_fma_f32 v[122:123], v[122:123], v[122:123], v[120:121]
	v_mov_b32_e32 v120, v14
	v_mov_b32_e32 v121, v10
	v_pk_fma_f32 v[122:123], v[120:121], v[120:121], v[122:123]
	v_mov_b32_e32 v120, v15
	v_mov_b32_e32 v121, v11
	v_pk_fma_f32 v[50:51], v[120:121], v[120:121], v[122:123]
	s_nop 0
	v_add_f32_e32 v16, v50, v51
	s_waitcnt vmcnt(9)
	v_mov_b32_e32 v54, v5
	s_waitcnt vmcnt(8)
	v_mov_b32_e32 v55, v1
	v_mov_b32_e32 v52, v4
	v_mov_b32_e32 v53, v0
	v_pk_mul_f32 v[54:55], v[54:55], v[54:55]
	s_nop 0
	v_pk_fma_f32 v[52:53], v[52:53], v[52:53], v[54:55]
	v_mov_b32_e32 v54, v6
	v_mov_b32_e32 v55, v2
	v_pk_fma_f32 v[52:53], v[54:55], v[54:55], v[52:53]
	v_mov_b32_e32 v54, v7
	v_mov_b32_e32 v55, v3
	v_pk_fma_f32 v[52:53], v[54:55], v[54:55], v[52:53]
	s_nop 0
	v_add_f32_e32 v16, v16, v52
	v_add_f32_e32 v16, v16, v53
	ds_bpermute_b32 v50, v43, v16
	s_waitcnt lgkmcnt(0)
	v_add_f32_e32 v16, v16, v50
	ds_bpermute_b32 v50, v44, v16
	s_waitcnt lgkmcnt(0)
	v_add_f32_e32 v16, v16, v50
	s_nop 1
	v_add_f32_dpp v16, v16, v16 row_ror:8 row_mask:0xf bank_mask:0xf
	ds_bpermute_b32 v50, v46, v16
	s_waitcnt lgkmcnt(0)
	v_add_f32_e32 v16, v16, v50
	s_nop 1
	v_add_f32_dpp v16, v16, v16 quad_perm:[2,3,0,1] row_mask:0xf bank_mask:0xf
	s_nop 1
	v_add_f32_dpp v16, v16, v16 quad_perm:[1,0,3,2] row_mask:0xf bank_mask:0xf
	v_fmamk_f32 v16, v16, 0x3a800000, v49
	v_cmp_gt_f32_e32 vcc, s4, v16
	v_mul_f32_e32 v50, 0x4b800000, v16
	s_mov_b32 s4, 0x2200000
	v_cndmask_b32_e32 v16, v16, v50, vcc
	v_rsq_f32_e32 v16, v16
	s_nop 0
	v_mul_f32_e32 v50, 0x45800000, v16
	v_cndmask_b32_e32 v16, v16, v50, vcc
	v_add_u32_e32 v50, v40, v41
	v_mad_i64_i32 v[40:41], s[4:5], v50, s4, v[28:29]
	v_mul_i32_i24_e32 v50, 0x4400, v50
	v_sub_u32_e32 v50, v42, v50
	v_ashrrev_i32_e32 v51, 31, v50
	v_lshlrev_b64 v[50:51], 11, v[50:51]
	v_lshl_add_u64 v[62:63], v[40:41], 0, v[50:51]
	s_waitcnt vmcnt(0)
	v_pk_mul_f32 v[12:13], v[12:13], v[16:17] op_sel_hi:[1,0]
	v_pk_mul_f32 v[14:15], v[14:15], v[16:17] op_sel_hi:[1,0]
	v_pk_mul_f32 v[8:9], v[8:9], v[16:17] op_sel_hi:[1,0]
	v_pk_mul_f32 v[10:11], v[10:11], v[16:17] op_sel_hi:[1,0]
	v_pk_mul_f32 v[4:5], v[4:5], v[16:17] op_sel_hi:[1,0]
	v_pk_mul_f32 v[6:7], v[6:7], v[16:17] op_sel_hi:[1,0]
	v_pk_mul_f32 v[0:1], v[0:1], v[16:17] op_sel_hi:[1,0]
	v_pk_mul_f32 v[2:3], v[2:3], v[16:17] op_sel_hi:[1,0]
	v_lshl_add_u64 v[126:127], v[62:63], 0, v[30:31]
	v_add_u32_e32 v42, s6, v42
	v_pk_mul_f32 v[12:13], v[104:105], v[12:13]
	v_pk_mul_f32 v[14:15], v[106:107], v[14:15]
	v_pk_add_f32 v[50:51], v[88:89], 1.0 op_sel_hi:[1,0]
	v_pk_add_f32 v[52:53], v[90:91], 1.0 op_sel_hi:[1,0]
	v_pk_mul_f32 v[8:9], v[8:9], v[108:109]
	v_pk_fma_f32 v[12:13], v[50:51], v[12:13], v[72:73]
	v_pk_fma_f32 v[14:15], v[52:53], v[14:15], v[74:75]
	v_pk_mul_f32 v[10:11], v[10:11], v[110:111]
	v_pk_add_f32 v[50:51], v[92:93], 1.0 op_sel_hi:[1,0]
	v_cvt_pk_bf16_f32 v120, v12, v13
	v_cvt_pk_bf16_f32 v121, v14, v15
	global_store_dwordx2 v[126:127], v[120:121], off
	v_pk_add_f32 v[52:53], v[94:95], 1.0 op_sel_hi:[1,0]
	v_pk_fma_f32 v[8:9], v[8:9], v[50:51], v[76:77]
	v_pk_mul_f32 v[4:5], v[4:5], v[112:113]
	v_pk_fma_f32 v[10:11], v[10:11], v[52:53], v[78:79]
	v_pk_mul_f32 v[6:7], v[6:7], v[114:115]
	v_pk_add_f32 v[50:51], v[96:97], 1.0 op_sel_hi:[1,0]
	v_cvt_pk_bf16_f32 v122, v8, v9
	v_cvt_pk_bf16_f32 v123, v10, v11
	global_store_dwordx2 v[126:127], v[122:123], off offset:512
	v_pk_add_f32 v[52:53], v[98:99], 1.0 op_sel_hi:[1,0]
	v_pk_fma_f32 v[4:5], v[4:5], v[50:51], v[80:81]
	v_pk_mul_f32 v[0:1], v[0:1], v[116:117]
	v_pk_fma_f32 v[6:7], v[6:7], v[52:53], v[82:83]
	v_pk_mul_f32 v[2:3], v[2:3], v[118:119]
	v_pk_add_f32 v[50:51], v[100:101], 1.0 op_sel_hi:[1,0]
	v_cvt_pk_bf16_f32 v124, v4, v5
	v_cvt_pk_bf16_f32 v125, v6, v7
	global_store_dwordx2 v[126:127], v[124:125], off offset:1024
	v_pk_add_f32 v[52:53], v[102:103], 1.0 op_sel_hi:[1,0]
	v_pk_fma_f32 v[0:1], v[0:1], v[50:51], v[84:85]
	s_mov_b32 s4, 0x87ff
	v_cmp_lt_i32_e32 vcc, s4, v42
	v_pk_fma_f32 v[2:3], v[2:3], v[52:53], v[86:87]
	s_or_b64 s[2:3], vcc, s[2:3]
	v_cvt_pk_bf16_f32 v0, v0, v1
	s_nop 0
	v_cvt_pk_bf16_f32 v1, v2, v3
	global_store_dwordx2 v[126:127], v[0:1], off offset:1536
	s_andn2_b64 exec, exec, s[2:3]
	s_cbranch_execz .LBB0_625

.LBB0_1290:
	v_ashrrev_i32_e32 v1, 31, v0
	v_lshlrev_b64 v[14:15], 12, v[0:1]
	v_lshl_add_u64 v[34:35], v[4:5], 0, v[14:15]
	global_load_dwordx4 v[14:17], v[34:35], off
	global_load_dwordx4 v[18:21], v[34:35], off offset:1024
	global_load_dwordx4 v[22:25], v[34:35], off offset:2048
	global_load_dwordx4 v[26:29], v[34:35], off offset:3072
	v_add_u32_e32 v0, s4, v0
	s_waitcnt vmcnt(3)
	v_mov_b32_e32 v38, v15
	s_waitcnt vmcnt(2)
	v_mov_b32_e32 v39, v19
	v_mov_b32_e32 v36, v14
	v_mov_b32_e32 v37, v18
	s_waitcnt vmcnt(1)
	v_mov_b32_e32 v46, v23
	s_waitcnt vmcnt(0)
	v_mov_b32_e32 v47, v27
	v_pk_mul_f32 v[38:39], v[38:39], v[38:39]
	v_mov_b32_e32 v40, v16
	v_mov_b32_e32 v41, v20
	v_mov_b32_e32 v44, v22
	v_mov_b32_e32 v45, v26
	v_pk_mul_f32 v[46:47], v[46:47], v[46:47]
	v_pk_fma_f32 v[36:37], v[36:37], v[36:37], v[38:39]
	v_mov_b32_e32 v42, v17
	v_mov_b32_e32 v43, v21
	v_mov_b32_e32 v48, v24
	v_mov_b32_e32 v49, v28
	v_pk_fma_f32 v[38:39], v[44:45], v[44:45], v[46:47]
	v_pk_fma_f32 v[36:37], v[40:41], v[40:41], v[36:37]
	v_mov_b32_e32 v50, v25
	v_mov_b32_e32 v51, v29
	v_pk_fma_f32 v[38:39], v[48:49], v[48:49], v[38:39]
	v_pk_fma_f32 v[36:37], v[42:43], v[42:43], v[36:37]
	v_pk_fma_f32 v[38:39], v[50:51], v[50:51], v[38:39]
	v_add_f32_e32 v1, v36, v37
	v_add_f32_e32 v1, v1, v38
	v_add_f32_e32 v1, v1, v39
	ds_bpermute_b32 v13, v6, v1
	s_waitcnt lgkmcnt(0)
	v_add_f32_e32 v1, v1, v13
	ds_bpermute_b32 v13, v7, v1
	s_waitcnt lgkmcnt(0)
	v_add_f32_e32 v1, v1, v13
	s_nop 1
	v_add_f32_dpp v1, v1, v1 row_ror:8 row_mask:0xf bank_mask:0xf
	ds_bpermute_b32 v13, v9, v1
	s_waitcnt lgkmcnt(0)
	v_add_f32_e32 v1, v1, v13
	s_nop 1
	v_add_f32_dpp v1, v1, v1 quad_perm:[2,3,0,1] row_mask:0xf bank_mask:0xf
	s_nop 1
	v_add_f32_dpp v1, v1, v1 quad_perm:[1,0,3,2] row_mask:0xf bank_mask:0xf
	v_fmamk_f32 v1, v1, 0x3a800000, v12
	v_mul_f32_e32 v13, 0x4b800000, v1
	v_cmp_gt_f32_e32 vcc, s5, v1
	s_nop 1
	v_cndmask_b32_e32 v1, v1, v13, vcc
	v_rsq_f32_e32 v1, v1
	s_nop 0
	v_mul_f32_e32 v13, 0x45800000, v1
	v_cndmask_b32_e32 v36, v1, v13, vcc
	v_pk_mul_f32 v[14:15], v[14:15], v[36:37] op_sel_hi:[1,0]
	v_pk_mul_f32 v[16:17], v[16:17], v[36:37] op_sel_hi:[1,0]
	v_pk_mul_f32 v[18:19], v[18:19], v[36:37] op_sel_hi:[1,0]
	v_pk_mul_f32 v[20:21], v[20:21], v[36:37] op_sel_hi:[1,0]
	v_pk_mul_f32 v[22:23], v[22:23], v[36:37] op_sel_hi:[1,0]
	v_pk_mul_f32 v[24:25], v[24:25], v[36:37] op_sel_hi:[1,0]
	v_pk_mul_f32 v[26:27], v[26:27], v[36:37] op_sel_hi:[1,0]
	v_pk_mul_f32 v[28:29], v[28:29], v[36:37] op_sel_hi:[1,0]
	v_pk_mul_f32 v[14:15], v[52:53], v[14:15]
	v_pk_mul_f32 v[16:17], v[54:55], v[16:17]
	v_pk_mul_f32 v[18:19], v[56:57], v[18:19]
	v_pk_mul_f32 v[20:21], v[58:59], v[20:21]
	v_pk_mul_f32 v[22:23], v[22:23], v[60:61]
	v_pk_mul_f32 v[24:25], v[24:25], v[62:63]
	v_pk_mul_f32 v[26:27], v[26:27], v[64:65]
	v_pk_mul_f32 v[28:29], v[28:29], v[66:67]
	v_cmp_lt_i32_e32 vcc, s6, v0
	s_or_b64 s[2:3], vcc, s[2:3]
	global_store_dwordx4 v[34:35], v[14:17], off
	global_store_dwordx4 v[34:35], v[18:21], off offset:1024
	global_store_dwordx4 v[34:35], v[22:25], off offset:2048
	global_store_dwordx4 v[34:35], v[26:29], off offset:3072
	s_andn2_b64 exec, exec, s[2:3]
	s_cbranch_execnz .LBB0_1290
